# stacked: static GEMM priority + 64-bit accumulator zeroing + attention prologue wait moved (on top of the prep2/prep1/transposes/scan/epilogue de-serialisations)
# speedup vs baseline: 1.0077x; 1.0005x over previous
; template <class Epi, class Sched, bool ALIGN_EPI = false, bool SP2 = false>
; __device__ __forceinline__ void gemm_phase(PG8_LAS unsigned char* lds, const Gemm g, const Sched& S, const Epi& E) {
;     ...
; #pragma unroll
;         for (int a = 0; a < 2; ++a)
; #pragma unroll
;             for (int b = 0; b < 2; ++b)
; #pragma unroll
;                 for (int m = 0; m < 4; ++m)
; #pragma unroll
;                     for (int n = 0; n < 2; ++n) acc[a][b][m][n] = (f32x4){0.f, 0.f, 0.f, 0.f};
;         cur = nxt; cA = nA; cB = nB; ++ui;
.LBB0_388:
	s_add_i32 s28, s50, -2
	s_add_u32 s18, s18, 0x80
	s_addc_u32 s19, s19, 0
	s_add_u32 s29, s12, 0x100
	s_addc_u32 s43, s13, 0
	s_mov_b32 s12, 0
	v_mov_b64_e32 v[2:3], 0
	v_mov_b64_e32 v[4:5], 0
	v_mov_b64_e32 v[6:7], 0
	v_mov_b64_e32 v[8:9], 0
	v_mov_b64_e32 v[10:11], 0
	v_mov_b64_e32 v[12:13], 0
	v_mov_b64_e32 v[14:15], 0
	v_mov_b64_e32 v[16:17], 0
	v_mov_b64_e32 v[18:19], 0
	v_mov_b64_e32 v[20:21], 0
	v_mov_b64_e32 v[22:23], 0
	v_mov_b64_e32 v[24:25], 0
	v_mov_b64_e32 v[26:27], 0
	v_mov_b64_e32 v[28:29], 0
	v_mov_b64_e32 v[30:31], 0
	v_mov_b64_e32 v[32:33], 0
	v_mov_b64_e32 v[34:35], 0
	v_mov_b64_e32 v[36:37], 0
	v_mov_b64_e32 v[38:39], 0
	v_mov_b64_e32 v[40:41], 0
	v_mov_b64_e32 v[42:43], 0
	v_mov_b64_e32 v[44:45], 0
	v_mov_b64_e32 v[46:47], 0
	v_mov_b64_e32 v[48:49], 0
	v_mov_b64_e32 v[50:51], 0
	v_mov_b64_e32 v[52:53], 0
	v_mov_b64_e32 v[54:55], 0
	v_mov_b64_e32 v[56:57], 0
	v_mov_b64_e32 v[58:59], 0
	v_mov_b64_e32 v[60:61], 0
	v_mov_b64_e32 v[62:63], 0
	v_mov_b64_e32 v[64:65], 0
	v_mov_b64_e32 v[66:67], 0
	v_mov_b64_e32 v[68:69], 0
	v_mov_b64_e32 v[70:71], 0
	v_mov_b64_e32 v[72:73], 0
	v_mov_b64_e32 v[74:75], 0
	v_mov_b64_e32 v[76:77], 0
	v_mov_b64_e32 v[78:79], 0
	v_mov_b64_e32 v[80:81], 0
	v_mov_b64_e32 v[82:83], 0
	v_mov_b64_e32 v[84:85], 0
	v_mov_b64_e32 v[86:87], 0
	v_mov_b64_e32 v[88:89], 0
	v_mov_b64_e32 v[90:91], 0
	v_mov_b64_e32 v[92:93], 0
	v_mov_b64_e32 v[94:95], 0
	v_mov_b64_e32 v[96:97], 0
	v_mov_b64_e32 v[98:99], 0
	v_mov_b64_e32 v[100:101], 0
	v_mov_b64_e32 v[102:103], 0
	v_mov_b64_e32 v[104:105], 0
	v_mov_b64_e32 v[106:107], 0
	v_mov_b64_e32 v[108:109], 0
	v_mov_b64_e32 v[110:111], 0
	v_mov_b64_e32 v[112:113], 0
	v_mov_b64_e32 v[114:115], 0
	v_mov_b64_e32 v[116:117], 0
	v_mov_b64_e32 v[118:119], 0
	v_mov_b64_e32 v[120:121], 0
	v_mov_b64_e32 v[122:123], 0
	v_mov_b64_e32 v[124:125], 0
	v_mov_b64_e32 v[126:127], 0
	v_mov_b64_e32 v[128:129], 0
	s_and_b64 vcc, exec, s[40:41]
	s_cbranch_vccnz .Lprio_skip_0
	s_setprio 1

; template <class Epi, class Sched, bool ALIGN_EPI = false, bool SP2 = false>
; __device__ __forceinline__ void gemm_phase(PG8_LAS unsigned char* lds, const Gemm g, const Sched& S, const Epi& E) {
;     ...
; #pragma unroll
;         for (int a = 0; a < 2; ++a)
; #pragma unroll
;             for (int b = 0; b < 2; ++b)
; #pragma unroll
;                 for (int m = 0; m < 4; ++m)
; #pragma unroll
;                     for (int n = 0; n < 2; ++n) acc[a][b][m][n] = (f32x4){0.f, 0.f, 0.f, 0.f};
;         cur = nxt; cA = nA; cB = nB; ++ui;
.LBB0_415:
	s_add_i32 s50, s63, -2
	s_add_u32 s18, s12, 0x80
	s_addc_u32 s19, s13, 0
	s_add_u32 s28, s28, 0x100
	s_addc_u32 s29, s29, 0
	s_mov_b32 s12, 0
	v_mov_b64_e32 v[2:3], 0
	v_mov_b64_e32 v[4:5], 0
	v_mov_b64_e32 v[6:7], 0
	v_mov_b64_e32 v[8:9], 0
	v_mov_b64_e32 v[10:11], 0
	v_mov_b64_e32 v[12:13], 0
	v_mov_b64_e32 v[14:15], 0
	v_mov_b64_e32 v[16:17], 0
	v_mov_b64_e32 v[18:19], 0
	v_mov_b64_e32 v[20:21], 0
	v_mov_b64_e32 v[22:23], 0
	v_mov_b64_e32 v[24:25], 0
	v_mov_b64_e32 v[26:27], 0
	v_mov_b64_e32 v[28:29], 0
	v_mov_b64_e32 v[30:31], 0
	v_mov_b64_e32 v[32:33], 0
	v_mov_b64_e32 v[34:35], 0
	v_mov_b64_e32 v[36:37], 0
	v_mov_b64_e32 v[38:39], 0
	v_mov_b64_e32 v[40:41], 0
	v_mov_b64_e32 v[42:43], 0
	v_mov_b64_e32 v[44:45], 0
	v_mov_b64_e32 v[46:47], 0
	v_mov_b64_e32 v[48:49], 0
	v_mov_b64_e32 v[50:51], 0
	v_mov_b64_e32 v[52:53], 0
	v_mov_b64_e32 v[54:55], 0
	v_mov_b64_e32 v[56:57], 0
	v_mov_b64_e32 v[58:59], 0
	v_mov_b64_e32 v[60:61], 0
	v_mov_b64_e32 v[62:63], 0
	v_mov_b64_e32 v[64:65], 0
	v_mov_b64_e32 v[66:67], 0
	v_mov_b64_e32 v[68:69], 0
	v_mov_b64_e32 v[70:71], 0
	v_mov_b64_e32 v[72:73], 0
	v_mov_b64_e32 v[74:75], 0
	v_mov_b64_e32 v[76:77], 0
	v_mov_b64_e32 v[78:79], 0
	v_mov_b64_e32 v[80:81], 0
	v_mov_b64_e32 v[82:83], 0
	v_mov_b64_e32 v[84:85], 0
	v_mov_b64_e32 v[86:87], 0
	v_mov_b64_e32 v[88:89], 0
	v_mov_b64_e32 v[90:91], 0
	v_mov_b64_e32 v[92:93], 0
	v_mov_b64_e32 v[94:95], 0
	v_mov_b64_e32 v[96:97], 0
	v_mov_b64_e32 v[98:99], 0
	v_mov_b64_e32 v[100:101], 0
	v_mov_b64_e32 v[102:103], 0
	v_mov_b64_e32 v[104:105], 0
	v_mov_b64_e32 v[106:107], 0
	v_mov_b64_e32 v[108:109], 0
	v_mov_b64_e32 v[110:111], 0
	v_mov_b64_e32 v[112:113], 0
	v_mov_b64_e32 v[114:115], 0
	v_mov_b64_e32 v[116:117], 0
	v_mov_b64_e32 v[118:119], 0
	v_mov_b64_e32 v[120:121], 0
	v_mov_b64_e32 v[122:123], 0
	v_mov_b64_e32 v[124:125], 0
	v_mov_b64_e32 v[126:127], 0
	v_mov_b64_e32 v[128:129], 0
	s_and_b64 vcc, exec, s[30:31]
	s_cbranch_vccnz .Lprio_skip_1
	s_setprio 1

; template <class Epi, class Sched, bool ALIGN_EPI = false, bool SP2 = false>
; __device__ __forceinline__ void gemm_phase(PG8_LAS unsigned char* lds, const Gemm g, const Sched& S, const Epi& E) {
;     ...
; #pragma unroll
;         for (int a = 0; a < 2; ++a)
; #pragma unroll
;             for (int b = 0; b < 2; ++b)
; #pragma unroll
;                 for (int m = 0; m < 4; ++m)
; #pragma unroll
;                     for (int n = 0; n < 2; ++n) acc[a][b][m][n] = (f32x4){0.f, 0.f, 0.f, 0.f};
;         cur = nxt; cA = nA; cB = nB; ++ui;
.LBB0_455:
	s_add_i32 s19, s48, -2
	s_add_u32 s44, s44, 0x80
	s_addc_u32 s45, s45, 0
	s_add_u32 s69, s12, 0x100
	s_addc_u32 s72, s13, 0
	s_mov_b32 s12, 0
	v_mov_b64_e32 v[2:3], 0
	v_mov_b64_e32 v[4:5], 0
	v_mov_b64_e32 v[6:7], 0
	v_mov_b64_e32 v[8:9], 0
	v_mov_b64_e32 v[10:11], 0
	v_mov_b64_e32 v[12:13], 0
	v_mov_b64_e32 v[14:15], 0
	v_mov_b64_e32 v[16:17], 0
	v_mov_b64_e32 v[18:19], 0
	v_mov_b64_e32 v[20:21], 0
	v_mov_b64_e32 v[22:23], 0
	v_mov_b64_e32 v[24:25], 0
	v_mov_b64_e32 v[26:27], 0
	v_mov_b64_e32 v[28:29], 0
	v_mov_b64_e32 v[30:31], 0
	v_mov_b64_e32 v[32:33], 0
	v_mov_b64_e32 v[34:35], 0
	v_mov_b64_e32 v[36:37], 0
	v_mov_b64_e32 v[38:39], 0
	v_mov_b64_e32 v[40:41], 0
	v_mov_b64_e32 v[42:43], 0
	v_mov_b64_e32 v[44:45], 0
	v_mov_b64_e32 v[46:47], 0
	v_mov_b64_e32 v[48:49], 0
	v_mov_b64_e32 v[50:51], 0
	v_mov_b64_e32 v[52:53], 0
	v_mov_b64_e32 v[54:55], 0
	v_mov_b64_e32 v[56:57], 0
	v_mov_b64_e32 v[58:59], 0
	v_mov_b64_e32 v[60:61], 0
	v_mov_b64_e32 v[62:63], 0
	v_mov_b64_e32 v[64:65], 0
	v_mov_b64_e32 v[66:67], 0
	v_mov_b64_e32 v[68:69], 0
	v_mov_b64_e32 v[70:71], 0
	v_mov_b64_e32 v[72:73], 0
	v_mov_b64_e32 v[74:75], 0
	v_mov_b64_e32 v[76:77], 0
	v_mov_b64_e32 v[78:79], 0
	v_mov_b64_e32 v[80:81], 0
	v_mov_b64_e32 v[82:83], 0
	v_mov_b64_e32 v[84:85], 0
	v_mov_b64_e32 v[86:87], 0
	v_mov_b64_e32 v[88:89], 0
	v_mov_b64_e32 v[90:91], 0
	v_mov_b64_e32 v[92:93], 0
	v_mov_b64_e32 v[94:95], 0
	v_mov_b64_e32 v[96:97], 0
	v_mov_b64_e32 v[98:99], 0
	v_mov_b64_e32 v[100:101], 0
	v_mov_b64_e32 v[102:103], 0
	v_mov_b64_e32 v[104:105], 0
	v_mov_b64_e32 v[106:107], 0
	v_mov_b64_e32 v[108:109], 0
	v_mov_b64_e32 v[110:111], 0
	v_mov_b64_e32 v[112:113], 0
	v_mov_b64_e32 v[114:115], 0
	v_mov_b64_e32 v[116:117], 0
	v_mov_b64_e32 v[118:119], 0
	v_mov_b64_e32 v[120:121], 0
	v_mov_b64_e32 v[122:123], 0
	v_mov_b64_e32 v[124:125], 0
	v_mov_b64_e32 v[126:127], 0
	v_mov_b64_e32 v[128:129], 0
	s_and_b64 vcc, exec, s[40:41]
	s_cbranch_vccnz .Lprio_skip_2
	s_setprio 1
